# best + K-loop heads aligned to 64 bytes
# baseline (speedup 1.0000x reference)
; #define PG8_STAGE(bufoff, gbase, voff) do { _Pragma("unroll") for (int _i = 0; _i < 2; ++_i) \
;         __builtin_amdgcn_global_load_lds((const unsigned*)((const char*)(gbase) + (voff)[_i]), (PG8_LAS unsigned*)(lds + (bufoff) + ldsw + _i * 8192), 16, 0, 0); } while (0)
; #define PG8_LDA(dst, b, h) do { _Pragma("unroll") for (int m = 0; m < 4; ++m) _Pragma("unroll") for (int k = 0; k < 2; ++k) dst[m][k] = *(const PG8_LAS bf16x8*)(lds + PG8_SA(b, h) + aoff + m * 2048 + k * 1024); } while (0)
; #define PG8_LDB(dst, b, h) do { _Pragma("unroll") for (int n = 0; n < 2; ++n) _Pragma("unroll") for (int k = 0; k < 2; ++k) dst[n][k] = *(const PG8_LAS bf16x8*)(lds + PG8_SB(b, h) + boff + n * 2048 + k * 1024); } while (0)
; #define PG8_WAIT_V(n) asm volatile("s_waitcnt vmcnt(" #n ")" ::: "memory")
; #define PG8_WAIT_L(n) asm volatile("s_waitcnt lgkmcnt(" #n ")" ::: "memory")
; #define PG8_BAR __builtin_amdgcn_s_barrier()
; #define PG8_SCHED __builtin_amdgcn_sched_barrier(0)
; template <class Epi, class Sched, bool ALIGN_EPI = false, bool SP2 = false>
; __device__ __forceinline__ void gemm_phase(PG8_LAS unsigned char* lds, const Gemm g, const Sched& S, const Epi& E) {
;     ...
;         const char* nA = has_next ? (const char*)g.A + (size_t)nxt.pm * tstep : cA; const char* nB = has_next ? (const char*)g.Bt + (size_t)nxt.pn * tstep : cB;
;         for (int t = 0; t < nt; t += 2) {
;             const bool last = (t == nt - 2);
;             const char* a1 = cA + (size_t)(t + 1) * kstepA;
;             const char* a2 = last ? nA : cA + (size_t)(t + 2) * kstepA; const char* b2 = last ? nB : cB + (size_t)(t + 2) * kstep;
;             const char* a3 = a2 + kstepA; const char* b3 = b2 + kstep;
;             if (last && has_next) S.a_ready(nxt);
;             if constexpr (SP2) {
;             PG8_LDB(B0, 0, 0); PG8_LDB(B1, 0, 1); PG8_SCHED; PG8_LDA(At, 0, 0); PG8_STAGE(PG8_SA(1, 1), a1 + hstep, voffA);
;             PG8_WAIT_V(8); PG8_WAIT_L(0); PG8_BAR; PG8_MMA(0, 0, At, B0); PG8_MMA(0, 1, At, B1); PG8_BAR; PG8_SCHED;
;             PG8_LDA(At, 0, 1); PG8_STAGE(PG8_SB(0, 0), b2, voffB); PG8_STAGE(PG8_SB(0, 1), b2 + hstep, voffB); PG8_STAGE(PG8_SA(0, 0), a2, voffA);
;             PG8_WAIT_V(8); PG8_WAIT_L(0); PG8_BAR; PG8_MMA(1, 0, At, B0); PG8_MMA(1, 1, At, B1); PG8_BAR; PG8_SCHED;
.LBB0_237:
	s_ashr_i32 s11, s10, 31
	s_lshl_b64 s[2:3], s[10:11], 19
	s_add_u32 s12, s52, s2
	s_addc_u32 s13, s53, s3
	s_and_b64 s[2:3], s[40:41], exec
	s_cselect_b32 s11, s13, s25
	s_cselect_b32 s67, s12, s24
	s_ashr_i32 s9, s8, 31
	s_lshl_b64 s[2:3], s[8:9], 19
	s_add_u32 s44, s54, s2
	s_addc_u32 s45, s55, s3
	s_and_b64 s[2:3], s[40:41], exec
	s_cselect_b32 s9, s45, s27
	s_cselect_b32 s68, s44, s26
	s_add_u32 s69, s26, 0x100
	s_addc_u32 s70, s27, 0
	s_mov_b32 s71, -2
	s_add_u32 s2, s24, 0x8000
	s_addc_u32 s3, s25, 0
	s_cmp_eq_u32 s71, 12
	s_cselect_b32 s46, s67, s2
	s_cselect_b32 s47, s11, s3
	s_cselect_b32 s42, s68, s69
	s_cselect_b32 s43, s9, s70
	s_add_u32 s26, s46, 0x4000
	s_addc_u32 s27, s47, 0
	v_add_u32_e32 v148, s76, v150
	s_add_i32 s72, 0, 0x14000
	ds_read_b128 v[144:147], v148
	ds_read_b128 v[160:163], v148 offset:1024
	ds_read_b128 v[164:167], v148 offset:2048
	ds_read_b128 v[168:171], v148 offset:3072
	v_add_u32_e32 v148, s72, v150
	ds_read_b128 v[172:175], v148
	ds_read_b128 v[176:179], v148 offset:1024
	ds_read_b128 v[180:183], v148 offset:2048
	ds_read_b128 v[184:187], v148 offset:3072
	v_lshl_add_u64 v[148:149], s[24:25], 0, v[142:143]
	s_add_i32 m0, s23, 0xc000
	ds_read_b128 v[188:191], v152
	ds_read_b128 v[206:209], v152 offset:1024
	ds_read_b128 v[210:213], v152 offset:2048
	ds_read_b128 v[214:217], v152 offset:3072
	ds_read_b128 v[218:221], v152 offset:4096
	ds_read_b128 v[222:225], v152 offset:5120
	ds_read_b128 v[226:229], v152 offset:6144
	ds_read_b128 v[230:233], v152 offset:7168
	global_load_lds_dwordx4 v[148:149], off
	v_lshl_add_u64 v[148:149], s[24:25], 0, v[140:141]
	s_add_i32 m0, s23, 0xe000
	s_nop 0
	global_load_lds_dwordx4 v[148:149], off
	s_waitcnt vmcnt(8)
	s_waitcnt lgkmcnt(0)
	s_barrier
	v_mfma_f32_16x16x32_bf16 v[126:129], v[144:147], v[188:191], 0
	v_mfma_f32_16x16x32_bf16 v[126:129], v[160:163], v[206:209], v[126:129]
	v_mfma_f32_16x16x32_bf16 v[122:125], v[168:171], v[206:209], 0
	v_mfma_f32_16x16x32_bf16 v[122:125], v[164:167], v[188:191], v[122:125]
	v_mfma_f32_16x16x32_bf16 v[106:109], v[164:167], v[210:213], 0
	v_mfma_f32_16x16x32_bf16 v[106:109], v[168:171], v[214:217], v[106:109]
	v_mfma_f32_16x16x32_bf16 v[110:113], v[160:163], v[214:217], 0
	v_mfma_f32_16x16x32_bf16 v[110:113], v[144:147], v[210:213], v[110:113]
	v_mfma_f32_16x16x32_bf16 v[94:97], v[144:147], v[218:221], 0
	v_mfma_f32_16x16x32_bf16 v[94:97], v[160:163], v[222:225], v[94:97]
	v_mfma_f32_16x16x32_bf16 v[90:93], v[168:171], v[222:225], 0
	v_mfma_f32_16x16x32_bf16 v[90:93], v[164:167], v[218:221], v[90:93]
	v_mfma_f32_16x16x32_bf16 v[74:77], v[164:167], v[226:229], 0
	v_mfma_f32_16x16x32_bf16 v[74:77], v[168:171], v[230:233], v[74:77]
	v_mfma_f32_16x16x32_bf16 v[78:81], v[160:163], v[230:233], 0
	v_mfma_f32_16x16x32_bf16 v[78:81], v[144:147], v[226:229], v[78:81]
	v_mfma_f32_16x16x32_bf16 v[118:121], v[172:175], v[188:191], 0
	v_mfma_f32_16x16x32_bf16 v[118:121], v[176:179], v[206:209], v[118:121]
	v_mfma_f32_16x16x32_bf16 v[114:117], v[184:187], v[206:209], 0
	v_mfma_f32_16x16x32_bf16 v[114:117], v[180:183], v[188:191], v[114:117]
	v_mfma_f32_16x16x32_bf16 v[98:101], v[180:183], v[210:213], 0
	v_mfma_f32_16x16x32_bf16 v[98:101], v[184:187], v[214:217], v[98:101]
	v_mfma_f32_16x16x32_bf16 v[102:105], v[176:179], v[214:217], 0
	v_mfma_f32_16x16x32_bf16 v[102:105], v[172:175], v[210:213], v[102:105]
	v_mfma_f32_16x16x32_bf16 v[86:89], v[172:175], v[218:221], 0
	v_mfma_f32_16x16x32_bf16 v[86:89], v[176:179], v[222:225], v[86:89]
	v_mfma_f32_16x16x32_bf16 v[82:85], v[184:187], v[222:225], 0
	v_mfma_f32_16x16x32_bf16 v[82:85], v[180:183], v[218:221], v[82:85]
	v_mfma_f32_16x16x32_bf16 v[66:69], v[180:183], v[226:229], 0
	v_mfma_f32_16x16x32_bf16 v[66:69], v[184:187], v[230:233], v[66:69]
	v_mfma_f32_16x16x32_bf16 v[70:73], v[176:179], v[230:233], 0
	v_mfma_f32_16x16x32_bf16 v[70:73], v[172:175], v[226:229], v[70:73]
	s_barrier
	s_add_i32 s24, s76, s51
	v_lshl_add_u64 v[148:149], s[42:43], 0, v[132:133]
	s_mov_b32 m0, s24
	ds_read_b128 v[188:191], v152 offset:16384
	ds_read_b128 v[206:209], v152 offset:17408
	ds_read_b128 v[210:213], v152 offset:18432
	ds_read_b128 v[214:217], v152 offset:19456
	ds_read_b128 v[218:221], v152 offset:20480
	ds_read_b128 v[222:225], v152 offset:21504
	ds_read_b128 v[226:229], v152 offset:22528
	ds_read_b128 v[230:233], v152 offset:23552
	global_load_lds_dwordx4 v[148:149], off
	s_add_i32 m0, s24, 0x2000
	s_add_u32 s24, s42, 0x40000
	v_lshl_add_u64 v[234:235], s[42:43], 0, v[136:137]
	s_addc_u32 s25, s43, 0
	s_add_i32 s72, s72, s51
	global_load_lds_dwordx4 v[234:235], off
	v_lshl_add_u64 v[236:237], s[24:25], 0, v[132:133]
	s_mov_b32 m0, s72
	s_nop 0
	global_load_lds_dwordx4 v[236:237], off
	v_lshl_add_u64 v[236:237], s[24:25], 0, v[136:137]
	s_add_i32 m0, s72, 0x2000
	s_nop 0
	global_load_lds_dwordx4 v[236:237], off
	v_lshl_add_u64 v[236:237], s[46:47], 0, v[130:131]
	s_mov_b32 m0, s23
	s_nop 0
	global_load_lds_dwordx4 v[236:237], off
	v_lshl_add_u64 v[236:237], s[46:47], 0, v[134:135]
	s_mov_b32 m0, s56
	s_nop 0
	global_load_lds_dwordx4 v[236:237], off
	s_waitcnt vmcnt(8)
	s_waitcnt lgkmcnt(0)
	s_barrier
; #define PG8_STAGE(bufoff, gbase, voff) do { _Pragma("unroll") for (int _i = 0; _i < 2; ++_i) \
;         __builtin_amdgcn_global_load_lds((const unsigned*)((const char*)(gbase) + (voff)[_i]), (PG8_LAS unsigned*)(lds + (bufoff) + ldsw + _i * 8192), 16, 0, 0); } while (0)
; #define PG8_LDA(dst, b, h) do { _Pragma("unroll") for (int m = 0; m < 4; ++m) _Pragma("unroll") for (int k = 0; k < 2; ++k) dst[m][k] = *(const PG8_LAS bf16x8*)(lds + PG8_SA(b, h) + aoff + m * 2048 + k * 1024); } while (0)
; #define PG8_LDB(dst, b, h) do { _Pragma("unroll") for (int n = 0; n < 2; ++n) _Pragma("unroll") for (int k = 0; k < 2; ++k) dst[n][k] = *(const PG8_LAS bf16x8*)(lds + PG8_SB(b, h) + boff + n * 2048 + k * 1024); } while (0)
; #define PG8_MMA(ai, bj, At, Bt) do { __builtin_amdgcn_s_setprio(1); _Pragma("unroll") for (int m = 0; m < 4; ++m) _Pragma("unroll") for (int n = 0; n < 2; ++n) _Pragma("unroll") for (int k = 0; k < 2; ++k) \
;         acc[ai][bj][m][n] = __builtin_amdgcn_mfma_f32_16x16x32_bf16(Bt[n][k], At[m][k], acc[ai][bj][m][n], 0, 0, 0); __builtin_amdgcn_s_setprio(0); } while (0)
; #define PG8_WAIT_V(n) asm volatile("s_waitcnt vmcnt(" #n ")" ::: "memory")
; #define PG8_WAIT_L(n) asm volatile("s_waitcnt lgkmcnt(" #n ")" ::: "memory")
; #define PG8_BAR __builtin_amdgcn_s_barrier()
; #define PG8_SCHED __builtin_amdgcn_sched_barrier(0)
; template <class Epi, class Sched, bool ALIGN_EPI = false, bool SP2 = false>
; __device__ __forceinline__ void gemm_phase(PG8_LAS unsigned char* lds, const Gemm g, const Sched& S, const Epi& E) {
;     ...
;             PG8_WAIT_V(8); PG8_WAIT_L(0); PG8_BAR; PG8_MMA(1, 0, At, B0); PG8_MMA(1, 1, At, B1); PG8_BAR; PG8_SCHED;
;             PG8_LDB(B0, 1, 0); PG8_LDB(B1, 1, 1); PG8_SCHED; PG8_LDA(At, 1, 0); PG8_STAGE(PG8_SA(0, 1), a2 + hstep, voffA);
;             PG8_WAIT_V(8); PG8_WAIT_L(0); PG8_BAR; PG8_MMA(0, 0, At, B0); PG8_MMA(0, 1, At, B1); PG8_BAR; PG8_SCHED;
	v_mfma_f32_16x16x32_bf16 v[62:65], v[144:147], v[188:191], 0
	v_mfma_f32_16x16x32_bf16 v[62:65], v[160:163], v[206:209], v[62:65]
	v_mfma_f32_16x16x32_bf16 v[58:61], v[168:171], v[206:209], 0
	v_mfma_f32_16x16x32_bf16 v[58:61], v[164:167], v[188:191], v[58:61]
	v_mfma_f32_16x16x32_bf16 v[42:45], v[164:167], v[210:213], 0
	v_mfma_f32_16x16x32_bf16 v[42:45], v[168:171], v[214:217], v[42:45]
	v_mfma_f32_16x16x32_bf16 v[46:49], v[160:163], v[214:217], 0
	v_mfma_f32_16x16x32_bf16 v[46:49], v[144:147], v[210:213], v[46:49]
	v_mfma_f32_16x16x32_bf16 v[30:33], v[144:147], v[218:221], 0
	v_mfma_f32_16x16x32_bf16 v[30:33], v[160:163], v[222:225], v[30:33]
	v_mfma_f32_16x16x32_bf16 v[26:29], v[168:171], v[222:225], 0
	v_mfma_f32_16x16x32_bf16 v[26:29], v[164:167], v[218:221], v[26:29]
	v_mfma_f32_16x16x32_bf16 v[10:13], v[164:167], v[226:229], 0
	v_mfma_f32_16x16x32_bf16 v[10:13], v[168:171], v[230:233], v[10:13]
	v_mfma_f32_16x16x32_bf16 v[14:17], v[160:163], v[230:233], 0
	v_mfma_f32_16x16x32_bf16 v[14:17], v[144:147], v[226:229], v[14:17]
	v_mfma_f32_16x16x32_bf16 v[54:57], v[172:175], v[188:191], 0
	v_mfma_f32_16x16x32_bf16 v[54:57], v[176:179], v[206:209], v[54:57]
	v_mfma_f32_16x16x32_bf16 v[50:53], v[184:187], v[206:209], 0
	v_mfma_f32_16x16x32_bf16 v[50:53], v[180:183], v[188:191], v[50:53]
	v_mfma_f32_16x16x32_bf16 v[34:37], v[180:183], v[210:213], 0
	v_mfma_f32_16x16x32_bf16 v[34:37], v[184:187], v[214:217], v[34:37]
	v_mfma_f32_16x16x32_bf16 v[38:41], v[176:179], v[214:217], 0
	v_mfma_f32_16x16x32_bf16 v[38:41], v[172:175], v[210:213], v[38:41]
	v_mfma_f32_16x16x32_bf16 v[22:25], v[172:175], v[218:221], 0
	v_mfma_f32_16x16x32_bf16 v[22:25], v[176:179], v[222:225], v[22:25]
	v_mfma_f32_16x16x32_bf16 v[18:21], v[184:187], v[222:225], 0
	v_mfma_f32_16x16x32_bf16 v[18:21], v[180:183], v[218:221], v[18:21]
	v_mfma_f32_16x16x32_bf16 v[2:5], v[180:183], v[226:229], 0
	v_mfma_f32_16x16x32_bf16 v[2:5], v[184:187], v[230:233], v[2:5]
	v_mfma_f32_16x16x32_bf16 v[6:9], v[176:179], v[230:233], 0
	v_mfma_f32_16x16x32_bf16 v[6:9], v[172:175], v[226:229], v[6:9]
	s_barrier
	s_add_i32 s72, 0, 0x18000
	v_add_u32_e32 v153, s72, v150
	s_add_i32 s73, 0, 0x1c000
	ds_read_b128 v[144:147], v153
	ds_read_b128 v[160:163], v153 offset:1024
	ds_read_b128 v[164:167], v153 offset:2048
	ds_read_b128 v[168:171], v153 offset:3072
	v_add_u32_e32 v153, s73, v150
	ds_read_b128 v[172:175], v153
	ds_read_b128 v[176:179], v153 offset:1024
	ds_read_b128 v[180:183], v153 offset:2048
	ds_read_b128 v[184:187], v153 offset:3072
	s_add_u32 s24, s46, 0x40000
	s_addc_u32 s25, s47, 0
	s_mov_b32 m0, s57
	v_lshl_add_u64 v[236:237], s[24:25], 0, v[130:131]
	ds_read_b128 v[188:191], v152 offset:32768
	ds_read_b128 v[206:209], v152 offset:33792
	ds_read_b128 v[210:213], v152 offset:34816
	ds_read_b128 v[214:217], v152 offset:35840
	ds_read_b128 v[218:221], v152 offset:36864
	ds_read_b128 v[222:225], v152 offset:37888
	ds_read_b128 v[226:229], v152 offset:38912
	ds_read_b128 v[230:233], v152 offset:39936
	global_load_lds_dwordx4 v[236:237], off
	v_lshl_add_u64 v[236:237], s[24:25], 0, v[134:135]
	s_mov_b32 m0, s58
	s_nop 0
	global_load_lds_dwordx4 v[236:237], off
	s_waitcnt vmcnt(8)
	s_waitcnt lgkmcnt(0)
	s_barrier
	v_mfma_f32_16x16x32_bf16 v[126:129], v[144:147], v[188:191], v[126:129]
	v_mfma_f32_16x16x32_bf16 v[126:129], v[160:163], v[206:209], v[126:129]
	v_mfma_f32_16x16x32_bf16 v[122:125], v[168:171], v[206:209], v[122:125]
	v_mfma_f32_16x16x32_bf16 v[122:125], v[164:167], v[188:191], v[122:125]
	v_mfma_f32_16x16x32_bf16 v[106:109], v[164:167], v[210:213], v[106:109]
	v_mfma_f32_16x16x32_bf16 v[106:109], v[168:171], v[214:217], v[106:109]
	v_mfma_f32_16x16x32_bf16 v[110:113], v[160:163], v[214:217], v[110:113]
	v_mfma_f32_16x16x32_bf16 v[110:113], v[144:147], v[210:213], v[110:113]
	v_mfma_f32_16x16x32_bf16 v[94:97], v[144:147], v[218:221], v[94:97]
	v_mfma_f32_16x16x32_bf16 v[94:97], v[160:163], v[222:225], v[94:97]
	v_mfma_f32_16x16x32_bf16 v[90:93], v[168:171], v[222:225], v[90:93]
	v_mfma_f32_16x16x32_bf16 v[90:93], v[164:167], v[218:221], v[90:93]
	v_mfma_f32_16x16x32_bf16 v[74:77], v[164:167], v[226:229], v[74:77]
	v_mfma_f32_16x16x32_bf16 v[74:77], v[168:171], v[230:233], v[74:77]
	v_mfma_f32_16x16x32_bf16 v[78:81], v[160:163], v[230:233], v[78:81]
	v_mfma_f32_16x16x32_bf16 v[78:81], v[144:147], v[226:229], v[78:81]
	v_mfma_f32_16x16x32_bf16 v[118:121], v[172:175], v[188:191], v[118:121]
	v_mfma_f32_16x16x32_bf16 v[118:121], v[176:179], v[206:209], v[118:121]
	v_mfma_f32_16x16x32_bf16 v[114:117], v[184:187], v[206:209], v[114:117]
	v_mfma_f32_16x16x32_bf16 v[114:117], v[180:183], v[188:191], v[114:117]
	v_mfma_f32_16x16x32_bf16 v[98:101], v[180:183], v[210:213], v[98:101]
	v_mfma_f32_16x16x32_bf16 v[98:101], v[184:187], v[214:217], v[98:101]
	v_mfma_f32_16x16x32_bf16 v[102:105], v[176:179], v[214:217], v[102:105]
	v_mfma_f32_16x16x32_bf16 v[102:105], v[172:175], v[210:213], v[102:105]
	v_mfma_f32_16x16x32_bf16 v[86:89], v[172:175], v[218:221], v[86:89]
	v_mfma_f32_16x16x32_bf16 v[86:89], v[176:179], v[222:225], v[86:89]
	v_mfma_f32_16x16x32_bf16 v[82:85], v[184:187], v[222:225], v[82:85]
	v_mfma_f32_16x16x32_bf16 v[82:85], v[180:183], v[218:221], v[82:85]
	v_mfma_f32_16x16x32_bf16 v[66:69], v[180:183], v[226:229], v[66:69]
	v_mfma_f32_16x16x32_bf16 v[66:69], v[184:187], v[230:233], v[66:69]
	v_mfma_f32_16x16x32_bf16 v[70:73], v[176:179], v[230:233], v[70:73]
	v_mfma_f32_16x16x32_bf16 v[70:73], v[172:175], v[226:229], v[70:73]
	s_barrier
; #define PG8_STAGE(bufoff, gbase, voff) do { _Pragma("unroll") for (int _i = 0; _i < 2; ++_i) \
;         __builtin_amdgcn_global_load_lds((const unsigned*)((const char*)(gbase) + (voff)[_i]), (PG8_LAS unsigned*)(lds + (bufoff) + ldsw + _i * 8192), 16, 0, 0); } while (0)
; #define PG8_LDA(dst, b, h) do { _Pragma("unroll") for (int m = 0; m < 4; ++m) _Pragma("unroll") for (int k = 0; k < 2; ++k) dst[m][k] = *(const PG8_LAS bf16x8*)(lds + PG8_SA(b, h) + aoff + m * 2048 + k * 1024); } while (0)
; #define PG8_MMA(ai, bj, At, Bt) do { __builtin_amdgcn_s_setprio(1); _Pragma("unroll") for (int m = 0; m < 4; ++m) _Pragma("unroll") for (int n = 0; n < 2; ++n) _Pragma("unroll") for (int k = 0; k < 2; ++k) \
;         acc[ai][bj][m][n] = __builtin_amdgcn_mfma_f32_16x16x32_bf16(Bt[n][k], At[m][k], acc[ai][bj][m][n], 0, 0, 0); __builtin_amdgcn_s_setprio(0); } while (0)
; #define PG8_WAIT_V(n) asm volatile("s_waitcnt vmcnt(" #n ")" ::: "memory")
; #define PG8_WAIT_L(n) asm volatile("s_waitcnt lgkmcnt(" #n ")" ::: "memory")
; #define PG8_BAR __builtin_amdgcn_s_barrier()
; #define PG8_SCHED __builtin_amdgcn_sched_barrier(0)
; template <class Epi, class Sched, bool ALIGN_EPI = false, bool SP2 = false>
; __device__ __forceinline__ void gemm_phase(PG8_LAS unsigned char* lds, const Gemm g, const Sched& S, const Epi& E) {
;     ...
;             PG8_LDA(At, 1, 1); PG8_STAGE(PG8_SB(1, 0), b3, voffB); PG8_STAGE(PG8_SB(1, 1), b3 + hstep, voffB); PG8_STAGE(PG8_SA(1, 0), a3, voffA);
;             PG8_WAIT_V(8); PG8_WAIT_L(0); PG8_BAR; PG8_MMA(1, 0, At, B0); PG8_MMA(1, 1, At, B1); PG8_BAR; PG8_SCHED;
	s_add_i32 s24, s72, s51
	v_lshl_add_u64 v[148:149], v[148:149], 0, s[38:39]
	s_mov_b32 m0, s24
	ds_read_b128 v[188:191], v152 offset:49152
	ds_read_b128 v[206:209], v152 offset:50176
	ds_read_b128 v[210:213], v152 offset:51200
	ds_read_b128 v[214:217], v152 offset:52224
	ds_read_b128 v[218:221], v152 offset:53248
	ds_read_b128 v[222:225], v152 offset:54272
	ds_read_b128 v[226:229], v152 offset:55296
	ds_read_b128 v[230:233], v152 offset:56320
	global_load_lds_dwordx4 v[148:149], off
	s_add_i32 m0, s24, 0x2000
	s_add_u32 s24, s42, 0x40080
	v_lshl_add_u64 v[148:149], v[234:235], 0, s[38:39]
	s_addc_u32 s25, s43, 0
	s_add_i32 s42, s73, s51
	global_load_lds_dwordx4 v[148:149], off
	v_lshl_add_u64 v[148:149], s[24:25], 0, v[132:133]
	s_mov_b32 m0, s42
	s_nop 0
	global_load_lds_dwordx4 v[148:149], off
	v_lshl_add_u64 v[148:149], s[24:25], 0, v[136:137]
	s_add_i32 m0, s42, 0x2000
	s_nop 0
	global_load_lds_dwordx4 v[148:149], off
	v_lshl_add_u64 v[148:149], s[26:27], 0, v[130:131]
	s_mov_b32 m0, s64
	s_nop 0
	global_load_lds_dwordx4 v[148:149], off
	v_lshl_add_u64 v[148:149], s[26:27], 0, v[134:135]
	s_mov_b32 m0, s65
	s_nop 0
	global_load_lds_dwordx4 v[148:149], off
	s_waitcnt vmcnt(8)
	s_waitcnt lgkmcnt(0)
	s_barrier
	v_mfma_f32_16x16x32_bf16 v[62:65], v[144:147], v[188:191], v[62:65]
	v_mfma_f32_16x16x32_bf16 v[62:65], v[160:163], v[206:209], v[62:65]
	v_mfma_f32_16x16x32_bf16 v[58:61], v[168:171], v[206:209], v[58:61]
	v_mfma_f32_16x16x32_bf16 v[58:61], v[164:167], v[188:191], v[58:61]
	v_mfma_f32_16x16x32_bf16 v[42:45], v[164:167], v[210:213], v[42:45]
	v_mfma_f32_16x16x32_bf16 v[42:45], v[168:171], v[214:217], v[42:45]
	v_mfma_f32_16x16x32_bf16 v[46:49], v[160:163], v[214:217], v[46:49]
	v_mfma_f32_16x16x32_bf16 v[46:49], v[144:147], v[210:213], v[46:49]
	v_mfma_f32_16x16x32_bf16 v[30:33], v[144:147], v[218:221], v[30:33]
	v_mfma_f32_16x16x32_bf16 v[30:33], v[160:163], v[222:225], v[30:33]
	v_mfma_f32_16x16x32_bf16 v[26:29], v[168:171], v[222:225], v[26:29]
	v_mfma_f32_16x16x32_bf16 v[26:29], v[164:167], v[218:221], v[26:29]
	v_mfma_f32_16x16x32_bf16 v[10:13], v[164:167], v[226:229], v[10:13]
	v_mfma_f32_16x16x32_bf16 v[10:13], v[168:171], v[230:233], v[10:13]
	v_mfma_f32_16x16x32_bf16 v[14:17], v[160:163], v[230:233], v[14:17]
	v_mfma_f32_16x16x32_bf16 v[14:17], v[144:147], v[226:229], v[14:17]
	v_mfma_f32_16x16x32_bf16 v[54:57], v[172:175], v[188:191], v[54:57]
	v_mfma_f32_16x16x32_bf16 v[54:57], v[176:179], v[206:209], v[54:57]
	v_mfma_f32_16x16x32_bf16 v[50:53], v[184:187], v[206:209], v[50:53]
	v_mfma_f32_16x16x32_bf16 v[50:53], v[180:183], v[188:191], v[50:53]
	v_mfma_f32_16x16x32_bf16 v[34:37], v[180:183], v[210:213], v[34:37]
	v_mfma_f32_16x16x32_bf16 v[34:37], v[184:187], v[214:217], v[34:37]
	v_mfma_f32_16x16x32_bf16 v[38:41], v[176:179], v[214:217], v[38:41]
	v_mfma_f32_16x16x32_bf16 v[38:41], v[172:175], v[210:213], v[38:41]
	v_mfma_f32_16x16x32_bf16 v[22:25], v[172:175], v[218:221], v[22:25]
	v_mfma_f32_16x16x32_bf16 v[22:25], v[176:179], v[222:225], v[22:25]
	v_mfma_f32_16x16x32_bf16 v[18:21], v[184:187], v[222:225], v[18:21]
	v_mfma_f32_16x16x32_bf16 v[18:21], v[180:183], v[218:221], v[18:21]
	v_mfma_f32_16x16x32_bf16 v[2:5], v[180:183], v[226:229], v[2:5]
	v_mfma_f32_16x16x32_bf16 v[2:5], v[184:187], v[230:233], v[2:5]
	v_mfma_f32_16x16x32_bf16 v[6:9], v[176:179], v[230:233], v[6:9]
	v_mfma_f32_16x16x32_bf16 v[6:9], v[172:175], v[226:229], v[6:9]
	s_barrier
	s_add_i32 s71, s71, 2
	s_add_u32 s69, s69, 0x100
	s_addc_u32 s70, s70, 0
	s_cmp_gt_u32 s71, 13
	s_mov_b64 s[24:25], s[2:3]
	s_cbranch_scc1 .Lpeel_exit_0
	.p2align 6

; #define PG8_STAGE(bufoff, gbase, voff) do { _Pragma("unroll") for (int _i = 0; _i < 2; ++_i) \
;         __builtin_amdgcn_global_load_lds((const unsigned*)((const char*)(gbase) + (voff)[_i]), (PG8_LAS unsigned*)(lds + (bufoff) + ldsw + _i * 8192), 16, 0, 0); } while (0)
; #define PG8_LDA(dst, b, h) do { _Pragma("unroll") for (int m = 0; m < 4; ++m) _Pragma("unroll") for (int k = 0; k < 2; ++k) dst[m][k] = *(const PG8_LAS bf16x8*)(lds + PG8_SA(b, h) + aoff + m * 2048 + k * 1024); } while (0)
; #define PG8_LDB(dst, b, h) do { _Pragma("unroll") for (int n = 0; n < 2; ++n) _Pragma("unroll") for (int k = 0; k < 2; ++k) dst[n][k] = *(const PG8_LAS bf16x8*)(lds + PG8_SB(b, h) + boff + n * 2048 + k * 1024); } while (0)
; #define PG8_WAIT_V(n) asm volatile("s_waitcnt vmcnt(" #n ")" ::: "memory")
; #define PG8_WAIT_L(n) asm volatile("s_waitcnt lgkmcnt(" #n ")" ::: "memory")
; #define PG8_BAR __builtin_amdgcn_s_barrier()
; #define PG8_SCHED __builtin_amdgcn_sched_barrier(0)
; template <class Epi, class Sched, bool ALIGN_EPI = false, bool SP2 = false>
; __device__ __forceinline__ void gemm_phase(PG8_LAS unsigned char* lds, const Gemm g, const Sched& S, const Epi& E) {
;     ...
;         const char* nA = has_next ? (const char*)g.A + (size_t)nxt.pm * tstep : cA; const char* nB = has_next ? (const char*)g.Bt + (size_t)nxt.pn * tstep : cB;
;         for (int t = 0; t < nt; t += 2) {
;             const bool last = (t == nt - 2);
;             const char* a1 = cA + (size_t)(t + 1) * kstepA;
;             const char* a2 = last ? nA : cA + (size_t)(t + 2) * kstepA; const char* b2 = last ? nB : cB + (size_t)(t + 2) * kstep;
;             const char* a3 = a2 + kstepA; const char* b3 = b2 + kstep;
;             if (last && has_next) S.a_ready(nxt);
;             if constexpr (SP2) {
;             PG8_LDB(B0, 0, 0); PG8_LDB(B1, 0, 1); PG8_SCHED; PG8_LDA(At, 0, 0); PG8_STAGE(PG8_SA(1, 1), a1 + hstep, voffA);
;             PG8_WAIT_V(8); PG8_WAIT_L(0); PG8_BAR; PG8_MMA(0, 0, At, B0); PG8_MMA(0, 1, At, B1); PG8_BAR; PG8_SCHED;
;             PG8_LDA(At, 0, 1); PG8_STAGE(PG8_SB(0, 0), b2, voffB); PG8_STAGE(PG8_SB(0, 1), b2 + hstep, voffB); PG8_STAGE(PG8_SA(0, 0), a2, voffA);
;             PG8_WAIT_V(8); PG8_WAIT_L(0); PG8_BAR; PG8_MMA(1, 0, At, B0); PG8_MMA(1, 1, At, B1); PG8_BAR; PG8_SCHED;
.LBB0_309:
	s_add_u32 s47, s24, 0x100
	s_addc_u32 s48, s25, 0
	s_add_u32 s2, s26, 0x4000
	s_addc_u32 s3, s27, 0
	s_mov_b32 s24, 0
	s_add_i32 s49, s24, 2
	s_add_u32 s25, s2, 0x4000
	s_addc_u32 s26, s3, 0
	s_cmp_eq_u32 s59, s24
	s_cselect_b32 s27, s9, s26
	s_cselect_b32 s26, s8, s25
	s_cselect_b32 s66, s44, s47
	s_cselect_b32 s67, s45, s48
	s_add_u32 s24, s26, 0x4000
	s_addc_u32 s25, s27, 0
	s_add_i32 s65, 0, 0x14000
	v_add_u32_e32 v142, s76, v187
	v_add_u32_e32 v167, s65, v187
	ds_read_b128 v[130:133], v142
	ds_read_b128 v[134:137], v142 offset:1024
	ds_read_b128 v[138:141], v142 offset:2048
	ds_read_b128 v[142:145], v142 offset:3072
	ds_read_b128 v[146:149], v167
	ds_read_b128 v[150:153], v167 offset:1024
	ds_read_b128 v[206:209], v167 offset:2048
	ds_read_b128 v[210:213], v167 offset:3072
	v_lshl_add_u64 v[184:185], s[2:3], 0, v[182:183]
	s_add_i32 m0, s51, 0xc000
	ds_read_b128 v[214:217], v188
	ds_read_b128 v[218:221], v188 offset:1024
	ds_read_b128 v[222:225], v188 offset:2048
	ds_read_b128 v[226:229], v188 offset:3072
	ds_read_b128 v[230:233], v188 offset:4096
	ds_read_b128 v[234:237], v188 offset:5120
	ds_read_b128 v[238:241], v188 offset:6144
	ds_read_b128 v[242:245], v188 offset:7168
	global_load_lds_dwordx4 v[184:185], off
	v_lshl_add_u64 v[184:185], s[2:3], 0, v[180:181]
	s_add_i32 m0, s51, 0xe000
	s_nop 0
	global_load_lds_dwordx4 v[184:185], off
	s_waitcnt vmcnt(8)
	s_waitcnt lgkmcnt(0)
	s_barrier
	v_mfma_f32_16x16x32_bf16 v[126:129], v[130:133], v[214:217], 0
	v_mfma_f32_16x16x32_bf16 v[126:129], v[134:137], v[218:221], v[126:129]
	v_mfma_f32_16x16x32_bf16 v[122:125], v[142:145], v[218:221], 0
	v_mfma_f32_16x16x32_bf16 v[122:125], v[138:141], v[214:217], v[122:125]
	v_mfma_f32_16x16x32_bf16 v[106:109], v[138:141], v[222:225], 0
	v_mfma_f32_16x16x32_bf16 v[106:109], v[142:145], v[226:229], v[106:109]
	v_mfma_f32_16x16x32_bf16 v[110:113], v[134:137], v[226:229], 0
	v_mfma_f32_16x16x32_bf16 v[110:113], v[130:133], v[222:225], v[110:113]
	v_mfma_f32_16x16x32_bf16 v[94:97], v[130:133], v[230:233], 0
	v_mfma_f32_16x16x32_bf16 v[94:97], v[134:137], v[234:237], v[94:97]
	v_mfma_f32_16x16x32_bf16 v[90:93], v[142:145], v[234:237], 0
	v_mfma_f32_16x16x32_bf16 v[90:93], v[138:141], v[230:233], v[90:93]
	v_mfma_f32_16x16x32_bf16 v[74:77], v[138:141], v[238:241], 0
	v_mfma_f32_16x16x32_bf16 v[74:77], v[142:145], v[242:245], v[74:77]
	v_mfma_f32_16x16x32_bf16 v[78:81], v[134:137], v[242:245], 0
	v_mfma_f32_16x16x32_bf16 v[78:81], v[130:133], v[238:241], v[78:81]
	v_mfma_f32_16x16x32_bf16 v[118:121], v[146:149], v[214:217], 0
	v_mfma_f32_16x16x32_bf16 v[118:121], v[150:153], v[218:221], v[118:121]
	v_mfma_f32_16x16x32_bf16 v[114:117], v[210:213], v[218:221], 0
	v_mfma_f32_16x16x32_bf16 v[114:117], v[206:209], v[214:217], v[114:117]
	v_mfma_f32_16x16x32_bf16 v[98:101], v[206:209], v[222:225], 0
	v_mfma_f32_16x16x32_bf16 v[98:101], v[210:213], v[226:229], v[98:101]
	v_mfma_f32_16x16x32_bf16 v[102:105], v[150:153], v[226:229], 0
	v_mfma_f32_16x16x32_bf16 v[102:105], v[146:149], v[222:225], v[102:105]
	v_mfma_f32_16x16x32_bf16 v[86:89], v[146:149], v[230:233], 0
	v_mfma_f32_16x16x32_bf16 v[86:89], v[150:153], v[234:237], v[86:89]
	v_mfma_f32_16x16x32_bf16 v[82:85], v[210:213], v[234:237], 0
	v_mfma_f32_16x16x32_bf16 v[82:85], v[206:209], v[230:233], v[82:85]
	v_mfma_f32_16x16x32_bf16 v[66:69], v[206:209], v[238:241], 0
	v_mfma_f32_16x16x32_bf16 v[66:69], v[210:213], v[242:245], v[66:69]
	v_mfma_f32_16x16x32_bf16 v[70:73], v[150:153], v[242:245], 0
	v_mfma_f32_16x16x32_bf16 v[70:73], v[146:149], v[238:241], v[70:73]
	s_barrier
	s_add_i32 s68, s76, s50
	v_lshl_add_u64 v[184:185], s[66:67], 0, v[0:1]
	s_mov_b32 m0, s68
	ds_read_b128 v[214:217], v188 offset:16384
	ds_read_b128 v[218:221], v188 offset:17408
	ds_read_b128 v[222:225], v188 offset:18432
	ds_read_b128 v[226:229], v188 offset:19456
	ds_read_b128 v[230:233], v188 offset:20480
	ds_read_b128 v[234:237], v188 offset:21504
	ds_read_b128 v[238:241], v188 offset:22528
	ds_read_b128 v[242:245], v188 offset:23552
	global_load_lds_dwordx4 v[184:185], off
	s_add_i32 m0, s68, 0x2000
	v_lshl_add_u64 v[190:191], s[66:67], 0, v[164:165]
	s_add_u32 s66, s66, s12
	s_addc_u32 s67, s67, 0
	s_add_i32 s65, s65, s50
	global_load_lds_dwordx4 v[190:191], off
	v_lshl_add_u64 v[246:247], s[66:67], 0, v[0:1]
	s_mov_b32 m0, s65
	v_lshl_add_u64 v[248:249], s[66:67], 0, v[164:165]
	global_load_lds_dwordx4 v[246:247], off
	s_add_i32 m0, s65, 0x2000
	v_lshl_add_u64 v[250:251], s[26:27], 0, v[160:161]
	global_load_lds_dwordx4 v[248:249], off
	s_mov_b32 m0, s51
	s_nop 0
	global_load_lds_dwordx4 v[250:251], off
	v_lshl_add_u64 v[250:251], s[26:27], 0, v[162:163]
	s_mov_b32 m0, s52
	s_nop 0
	global_load_lds_dwordx4 v[250:251], off
	s_waitcnt vmcnt(8)
	s_waitcnt lgkmcnt(0)
	s_barrier
; #define PG8_STAGE(bufoff, gbase, voff) do { _Pragma("unroll") for (int _i = 0; _i < 2; ++_i) \
;         __builtin_amdgcn_global_load_lds((const unsigned*)((const char*)(gbase) + (voff)[_i]), (PG8_LAS unsigned*)(lds + (bufoff) + ldsw + _i * 8192), 16, 0, 0); } while (0)
; #define PG8_LDA(dst, b, h) do { _Pragma("unroll") for (int m = 0; m < 4; ++m) _Pragma("unroll") for (int k = 0; k < 2; ++k) dst[m][k] = *(const PG8_LAS bf16x8*)(lds + PG8_SA(b, h) + aoff + m * 2048 + k * 1024); } while (0)
; #define PG8_LDB(dst, b, h) do { _Pragma("unroll") for (int n = 0; n < 2; ++n) _Pragma("unroll") for (int k = 0; k < 2; ++k) dst[n][k] = *(const PG8_LAS bf16x8*)(lds + PG8_SB(b, h) + boff + n * 2048 + k * 1024); } while (0)
; #define PG8_MMA(ai, bj, At, Bt) do { __builtin_amdgcn_s_setprio(1); _Pragma("unroll") for (int m = 0; m < 4; ++m) _Pragma("unroll") for (int n = 0; n < 2; ++n) _Pragma("unroll") for (int k = 0; k < 2; ++k) \
;         acc[ai][bj][m][n] = __builtin_amdgcn_mfma_f32_16x16x32_bf16(Bt[n][k], At[m][k], acc[ai][bj][m][n], 0, 0, 0); __builtin_amdgcn_s_setprio(0); } while (0)
; #define PG8_WAIT_V(n) asm volatile("s_waitcnt vmcnt(" #n ")" ::: "memory")
; #define PG8_WAIT_L(n) asm volatile("s_waitcnt lgkmcnt(" #n ")" ::: "memory")
; #define PG8_BAR __builtin_amdgcn_s_barrier()
; #define PG8_SCHED __builtin_amdgcn_sched_barrier(0)
; template <class Epi, class Sched, bool ALIGN_EPI = false, bool SP2 = false>
; __device__ __forceinline__ void gemm_phase(PG8_LAS unsigned char* lds, const Gemm g, const Sched& S, const Epi& E) {
;     ...
;             PG8_WAIT_V(8); PG8_WAIT_L(0); PG8_BAR; PG8_MMA(1, 0, At, B0); PG8_MMA(1, 1, At, B1); PG8_BAR; PG8_SCHED;
;             PG8_LDB(B0, 1, 0); PG8_LDB(B1, 1, 1); PG8_SCHED; PG8_LDA(At, 1, 0); PG8_STAGE(PG8_SA(0, 1), a2 + hstep, voffA);
;             PG8_WAIT_V(8); PG8_WAIT_L(0); PG8_BAR; PG8_MMA(0, 0, At, B0); PG8_MMA(0, 1, At, B1); PG8_BAR; PG8_SCHED;
	v_mfma_f32_16x16x32_bf16 v[62:65], v[130:133], v[214:217], 0
	v_mfma_f32_16x16x32_bf16 v[62:65], v[134:137], v[218:221], v[62:65]
	v_mfma_f32_16x16x32_bf16 v[58:61], v[142:145], v[218:221], 0
	v_mfma_f32_16x16x32_bf16 v[58:61], v[138:141], v[214:217], v[58:61]
	v_mfma_f32_16x16x32_bf16 v[42:45], v[138:141], v[222:225], 0
	v_mfma_f32_16x16x32_bf16 v[42:45], v[142:145], v[226:229], v[42:45]
	v_mfma_f32_16x16x32_bf16 v[46:49], v[134:137], v[226:229], 0
	v_mfma_f32_16x16x32_bf16 v[46:49], v[130:133], v[222:225], v[46:49]
	v_mfma_f32_16x16x32_bf16 v[30:33], v[130:133], v[230:233], 0
	v_mfma_f32_16x16x32_bf16 v[30:33], v[134:137], v[234:237], v[30:33]
	v_mfma_f32_16x16x32_bf16 v[26:29], v[142:145], v[234:237], 0
	v_mfma_f32_16x16x32_bf16 v[26:29], v[138:141], v[230:233], v[26:29]
	v_mfma_f32_16x16x32_bf16 v[10:13], v[138:141], v[238:241], 0
	v_mfma_f32_16x16x32_bf16 v[10:13], v[142:145], v[242:245], v[10:13]
	v_mfma_f32_16x16x32_bf16 v[14:17], v[134:137], v[242:245], 0
	v_mfma_f32_16x16x32_bf16 v[14:17], v[130:133], v[238:241], v[14:17]
	v_mfma_f32_16x16x32_bf16 v[54:57], v[146:149], v[214:217], 0
	v_mfma_f32_16x16x32_bf16 v[54:57], v[150:153], v[218:221], v[54:57]
	v_mfma_f32_16x16x32_bf16 v[50:53], v[210:213], v[218:221], 0
	v_mfma_f32_16x16x32_bf16 v[50:53], v[206:209], v[214:217], v[50:53]
	v_mfma_f32_16x16x32_bf16 v[34:37], v[206:209], v[222:225], 0
	v_mfma_f32_16x16x32_bf16 v[34:37], v[210:213], v[226:229], v[34:37]
	v_mfma_f32_16x16x32_bf16 v[38:41], v[150:153], v[226:229], 0
	v_mfma_f32_16x16x32_bf16 v[38:41], v[146:149], v[222:225], v[38:41]
	v_mfma_f32_16x16x32_bf16 v[22:25], v[146:149], v[230:233], 0
	v_mfma_f32_16x16x32_bf16 v[22:25], v[150:153], v[234:237], v[22:25]
	v_mfma_f32_16x16x32_bf16 v[18:21], v[210:213], v[234:237], 0
	v_mfma_f32_16x16x32_bf16 v[18:21], v[206:209], v[230:233], v[18:21]
	v_mfma_f32_16x16x32_bf16 v[2:5], v[206:209], v[238:241], 0
	v_mfma_f32_16x16x32_bf16 v[2:5], v[210:213], v[242:245], v[2:5]
	v_mfma_f32_16x16x32_bf16 v[6:9], v[150:153], v[242:245], 0
	v_mfma_f32_16x16x32_bf16 v[6:9], v[146:149], v[238:241], v[6:9]
	s_barrier
	s_add_i32 s65, 0, 0x18000
	s_add_i32 s66, 0, 0x1c000
	v_add_u32_e32 v142, s65, v187
	v_add_u32_e32 v167, s66, v187
	ds_read_b128 v[130:133], v142
	ds_read_b128 v[134:137], v142 offset:1024
	ds_read_b128 v[138:141], v142 offset:2048
	ds_read_b128 v[142:145], v142 offset:3072
	ds_read_b128 v[146:149], v167
	ds_read_b128 v[150:153], v167 offset:1024
	ds_read_b128 v[206:209], v167 offset:2048
	ds_read_b128 v[210:213], v167 offset:3072
	s_add_u32 s26, s26, s12
	s_addc_u32 s27, s27, 0
	s_mov_b32 m0, s53
	v_lshl_add_u64 v[250:251], s[26:27], 0, v[160:161]
	ds_read_b128 v[214:217], v188 offset:32768
	ds_read_b128 v[218:221], v188 offset:33792
	ds_read_b128 v[222:225], v188 offset:34816
	ds_read_b128 v[226:229], v188 offset:35840
	ds_read_b128 v[230:233], v188 offset:36864
	ds_read_b128 v[234:237], v188 offset:37888
	ds_read_b128 v[238:241], v188 offset:38912
	ds_read_b128 v[242:245], v188 offset:39936
	global_load_lds_dwordx4 v[250:251], off
	v_lshl_add_u64 v[250:251], s[26:27], 0, v[162:163]
	s_mov_b32 m0, s54
	s_nop 0
	global_load_lds_dwordx4 v[250:251], off
	s_waitcnt vmcnt(8)
	s_waitcnt lgkmcnt(0)
	s_barrier
	v_mfma_f32_16x16x32_bf16 v[126:129], v[130:133], v[214:217], v[126:129]
	v_mfma_f32_16x16x32_bf16 v[126:129], v[134:137], v[218:221], v[126:129]
	v_mfma_f32_16x16x32_bf16 v[122:125], v[142:145], v[218:221], v[122:125]
	v_mfma_f32_16x16x32_bf16 v[122:125], v[138:141], v[214:217], v[122:125]
	v_mfma_f32_16x16x32_bf16 v[106:109], v[138:141], v[222:225], v[106:109]
	v_mfma_f32_16x16x32_bf16 v[106:109], v[142:145], v[226:229], v[106:109]
	v_mfma_f32_16x16x32_bf16 v[110:113], v[134:137], v[226:229], v[110:113]
	v_mfma_f32_16x16x32_bf16 v[110:113], v[130:133], v[222:225], v[110:113]
	v_mfma_f32_16x16x32_bf16 v[94:97], v[130:133], v[230:233], v[94:97]
	v_mfma_f32_16x16x32_bf16 v[94:97], v[134:137], v[234:237], v[94:97]
	v_mfma_f32_16x16x32_bf16 v[90:93], v[142:145], v[234:237], v[90:93]
	v_mfma_f32_16x16x32_bf16 v[90:93], v[138:141], v[230:233], v[90:93]
	v_mfma_f32_16x16x32_bf16 v[74:77], v[138:141], v[238:241], v[74:77]
	v_mfma_f32_16x16x32_bf16 v[74:77], v[142:145], v[242:245], v[74:77]
	v_mfma_f32_16x16x32_bf16 v[78:81], v[134:137], v[242:245], v[78:81]
	v_mfma_f32_16x16x32_bf16 v[78:81], v[130:133], v[238:241], v[78:81]
	v_mfma_f32_16x16x32_bf16 v[118:121], v[146:149], v[214:217], v[118:121]
	v_mfma_f32_16x16x32_bf16 v[118:121], v[150:153], v[218:221], v[118:121]
	v_mfma_f32_16x16x32_bf16 v[114:117], v[210:213], v[218:221], v[114:117]
	v_mfma_f32_16x16x32_bf16 v[114:117], v[206:209], v[214:217], v[114:117]
	v_mfma_f32_16x16x32_bf16 v[98:101], v[206:209], v[222:225], v[98:101]
	v_mfma_f32_16x16x32_bf16 v[98:101], v[210:213], v[226:229], v[98:101]
	v_mfma_f32_16x16x32_bf16 v[102:105], v[150:153], v[226:229], v[102:105]
	v_mfma_f32_16x16x32_bf16 v[102:105], v[146:149], v[222:225], v[102:105]
	v_mfma_f32_16x16x32_bf16 v[86:89], v[146:149], v[230:233], v[86:89]
	v_mfma_f32_16x16x32_bf16 v[86:89], v[150:153], v[234:237], v[86:89]
	v_mfma_f32_16x16x32_bf16 v[82:85], v[210:213], v[234:237], v[82:85]
	v_mfma_f32_16x16x32_bf16 v[82:85], v[206:209], v[230:233], v[82:85]
	v_mfma_f32_16x16x32_bf16 v[66:69], v[206:209], v[238:241], v[66:69]
	v_mfma_f32_16x16x32_bf16 v[66:69], v[210:213], v[242:245], v[66:69]
	v_mfma_f32_16x16x32_bf16 v[70:73], v[150:153], v[242:245], v[70:73]
	v_mfma_f32_16x16x32_bf16 v[70:73], v[146:149], v[238:241], v[70:73]
	s_barrier
; #define PG8_STAGE(bufoff, gbase, voff) do { _Pragma("unroll") for (int _i = 0; _i < 2; ++_i) \
;         __builtin_amdgcn_global_load_lds((const unsigned*)((const char*)(gbase) + (voff)[_i]), (PG8_LAS unsigned*)(lds + (bufoff) + ldsw + _i * 8192), 16, 0, 0); } while (0)
; #define PG8_LDA(dst, b, h) do { _Pragma("unroll") for (int m = 0; m < 4; ++m) _Pragma("unroll") for (int k = 0; k < 2; ++k) dst[m][k] = *(const PG8_LAS bf16x8*)(lds + PG8_SA(b, h) + aoff + m * 2048 + k * 1024); } while (0)
; #define PG8_MMA(ai, bj, At, Bt) do { __builtin_amdgcn_s_setprio(1); _Pragma("unroll") for (int m = 0; m < 4; ++m) _Pragma("unroll") for (int n = 0; n < 2; ++n) _Pragma("unroll") for (int k = 0; k < 2; ++k) \
;         acc[ai][bj][m][n] = __builtin_amdgcn_mfma_f32_16x16x32_bf16(Bt[n][k], At[m][k], acc[ai][bj][m][n], 0, 0, 0); __builtin_amdgcn_s_setprio(0); } while (0)
; #define PG8_WAIT_V(n) asm volatile("s_waitcnt vmcnt(" #n ")" ::: "memory")
; #define PG8_WAIT_L(n) asm volatile("s_waitcnt lgkmcnt(" #n ")" ::: "memory")
; #define PG8_BAR __builtin_amdgcn_s_barrier()
; #define PG8_SCHED __builtin_amdgcn_sched_barrier(0)
; template <class Epi, class Sched, bool ALIGN_EPI = false, bool SP2 = false>
; __device__ __forceinline__ void gemm_phase(PG8_LAS unsigned char* lds, const Gemm g, const Sched& S, const Epi& E) {
;     ...
;         for (int t = 0; t < nt; t += 2) {
;     ...
;             PG8_LDA(At, 1, 1); PG8_STAGE(PG8_SB(1, 0), b3, voffB); PG8_STAGE(PG8_SB(1, 1), b3 + hstep, voffB); PG8_STAGE(PG8_SA(1, 0), a3, voffA);
;             PG8_WAIT_V(8); PG8_WAIT_L(0); PG8_BAR; PG8_MMA(1, 0, At, B0); PG8_MMA(1, 1, At, B1); PG8_BAR; PG8_SCHED;
	s_add_i32 s26, s65, s50
	v_lshl_add_u64 v[184:185], v[184:185], 0, s[38:39]
	s_mov_b32 m0, s26
	ds_read_b128 v[214:217], v188 offset:49152
	ds_read_b128 v[218:221], v188 offset:50176
	ds_read_b128 v[222:225], v188 offset:51200
	ds_read_b128 v[226:229], v188 offset:52224
	ds_read_b128 v[230:233], v188 offset:53248
	ds_read_b128 v[234:237], v188 offset:54272
	ds_read_b128 v[238:241], v188 offset:55296
	ds_read_b128 v[242:245], v188 offset:56320
	global_load_lds_dwordx4 v[184:185], off
	v_lshl_add_u64 v[184:185], v[190:191], 0, s[38:39]
	s_add_i32 m0, s26, 0x2000
	s_add_i32 s26, s66, s50
	global_load_lds_dwordx4 v[184:185], off
	v_lshl_add_u64 v[184:185], v[246:247], 0, s[38:39]
	s_mov_b32 m0, s26
	s_nop 0
	global_load_lds_dwordx4 v[184:185], off
	v_lshl_add_u64 v[184:185], v[248:249], 0, s[38:39]
	s_add_i32 m0, s26, 0x2000
	s_nop 0
	global_load_lds_dwordx4 v[184:185], off
	v_lshl_add_u64 v[184:185], s[24:25], 0, v[160:161]
	s_mov_b32 m0, s56
	s_nop 0
	global_load_lds_dwordx4 v[184:185], off
	v_lshl_add_u64 v[184:185], s[24:25], 0, v[162:163]
	s_mov_b32 m0, s57
	s_nop 0
	global_load_lds_dwordx4 v[184:185], off
	s_waitcnt vmcnt(8)
	s_waitcnt lgkmcnt(0)
	s_barrier
	v_mfma_f32_16x16x32_bf16 v[62:65], v[130:133], v[214:217], v[62:65]
	v_mfma_f32_16x16x32_bf16 v[62:65], v[134:137], v[218:221], v[62:65]
	v_mfma_f32_16x16x32_bf16 v[58:61], v[142:145], v[218:221], v[58:61]
	v_mfma_f32_16x16x32_bf16 v[58:61], v[138:141], v[214:217], v[58:61]
	v_mfma_f32_16x16x32_bf16 v[42:45], v[138:141], v[222:225], v[42:45]
	v_mfma_f32_16x16x32_bf16 v[42:45], v[142:145], v[226:229], v[42:45]
	v_mfma_f32_16x16x32_bf16 v[46:49], v[134:137], v[226:229], v[46:49]
	v_mfma_f32_16x16x32_bf16 v[46:49], v[130:133], v[222:225], v[46:49]
	v_mfma_f32_16x16x32_bf16 v[30:33], v[130:133], v[230:233], v[30:33]
	v_mfma_f32_16x16x32_bf16 v[30:33], v[134:137], v[234:237], v[30:33]
	v_mfma_f32_16x16x32_bf16 v[26:29], v[142:145], v[234:237], v[26:29]
	v_mfma_f32_16x16x32_bf16 v[26:29], v[138:141], v[230:233], v[26:29]
	v_mfma_f32_16x16x32_bf16 v[10:13], v[138:141], v[238:241], v[10:13]
	v_mfma_f32_16x16x32_bf16 v[10:13], v[142:145], v[242:245], v[10:13]
	v_mfma_f32_16x16x32_bf16 v[14:17], v[134:137], v[242:245], v[14:17]
	v_mfma_f32_16x16x32_bf16 v[14:17], v[130:133], v[238:241], v[14:17]
	v_mfma_f32_16x16x32_bf16 v[54:57], v[146:149], v[214:217], v[54:57]
	v_mfma_f32_16x16x32_bf16 v[54:57], v[150:153], v[218:221], v[54:57]
	v_mfma_f32_16x16x32_bf16 v[50:53], v[210:213], v[218:221], v[50:53]
	v_mfma_f32_16x16x32_bf16 v[50:53], v[206:209], v[214:217], v[50:53]
	v_mfma_f32_16x16x32_bf16 v[34:37], v[206:209], v[222:225], v[34:37]
	v_mfma_f32_16x16x32_bf16 v[34:37], v[210:213], v[226:229], v[34:37]
	v_mfma_f32_16x16x32_bf16 v[38:41], v[150:153], v[226:229], v[38:41]
	v_mfma_f32_16x16x32_bf16 v[38:41], v[146:149], v[222:225], v[38:41]
	v_mfma_f32_16x16x32_bf16 v[22:25], v[146:149], v[230:233], v[22:25]
	v_mfma_f32_16x16x32_bf16 v[22:25], v[150:153], v[234:237], v[22:25]
	v_mfma_f32_16x16x32_bf16 v[18:21], v[210:213], v[234:237], v[18:21]
	v_mfma_f32_16x16x32_bf16 v[18:21], v[206:209], v[230:233], v[18:21]
	v_mfma_f32_16x16x32_bf16 v[2:5], v[206:209], v[238:241], v[2:5]
	v_mfma_f32_16x16x32_bf16 v[2:5], v[210:213], v[242:245], v[2:5]
	v_mfma_f32_16x16x32_bf16 v[6:9], v[150:153], v[242:245], v[6:9]
	v_mfma_f32_16x16x32_bf16 v[6:9], v[146:149], v[238:241], v[6:9]
	s_barrier
	s_add_u32 s47, s47, 0x100
	s_addc_u32 s48, s48, 0
	s_add_u32 s2, s2, 0x8000
	s_addc_u32 s3, s3, 0
	s_cmp_ge_u32 s49, s55
	s_mov_b32 s24, s49
	s_cbranch_scc1 .Lpeel_exit_1
	.p2align 6

; #define PG8_STAGE(bufoff, gbase, voff) do { _Pragma("unroll") for (int _i = 0; _i < 2; ++_i) \
;         __builtin_amdgcn_global_load_lds((const unsigned*)((const char*)(gbase) + (voff)[_i]), (PG8_LAS unsigned*)(lds + (bufoff) + ldsw + _i * 8192), 16, 0, 0); } while (0)
; #define PG8_LDA(dst, b, h) do { _Pragma("unroll") for (int m = 0; m < 4; ++m) _Pragma("unroll") for (int k = 0; k < 2; ++k) dst[m][k] = *(const PG8_LAS bf16x8*)(lds + PG8_SA(b, h) + aoff + m * 2048 + k * 1024); } while (0)
; #define PG8_LDB(dst, b, h) do { _Pragma("unroll") for (int n = 0; n < 2; ++n) _Pragma("unroll") for (int k = 0; k < 2; ++k) dst[n][k] = *(const PG8_LAS bf16x8*)(lds + PG8_SB(b, h) + boff + n * 2048 + k * 1024); } while (0)
; #define PG8_WAIT_V(n) asm volatile("s_waitcnt vmcnt(" #n ")" ::: "memory")
; #define PG8_WAIT_L(n) asm volatile("s_waitcnt lgkmcnt(" #n ")" ::: "memory")
; #define PG8_BAR __builtin_amdgcn_s_barrier()
; #define PG8_SCHED __builtin_amdgcn_sched_barrier(0)
; template <class Epi, class Sched, bool ALIGN_EPI = false, bool SP2 = false>
; __device__ __forceinline__ void gemm_phase(PG8_LAS unsigned char* lds, const Gemm g, const Sched& S, const Epi& E) {
;     ...
;         const char* nA = has_next ? (const char*)g.A + (size_t)nxt.pm * tstep : cA; const char* nB = has_next ? (const char*)g.Bt + (size_t)nxt.pn * tstep : cB;
;         for (int t = 0; t < nt; t += 2) {
;             const bool last = (t == nt - 2);
;             const char* a1 = cA + (size_t)(t + 1) * kstepA;
;             const char* a2 = last ? nA : cA + (size_t)(t + 2) * kstepA; const char* b2 = last ? nB : cB + (size_t)(t + 2) * kstep;
;             const char* a3 = a2 + kstepA; const char* b3 = b2 + kstep;
;             if (last && has_next) S.a_ready(nxt);
;             if constexpr (SP2) {
;             PG8_LDB(B0, 0, 0); PG8_LDB(B1, 0, 1); PG8_SCHED; PG8_LDA(At, 0, 0); PG8_STAGE(PG8_SA(1, 1), a1 + hstep, voffA);
;             PG8_WAIT_V(8); PG8_WAIT_L(0); PG8_BAR; PG8_MMA(0, 0, At, B0); PG8_MMA(0, 1, At, B1); PG8_BAR; PG8_SCHED;
;             PG8_LDA(At, 0, 1); PG8_STAGE(PG8_SB(0, 0), b2, voffB); PG8_STAGE(PG8_SB(0, 1), b2 + hstep, voffB); PG8_STAGE(PG8_SA(0, 0), a2, voffA);
;             PG8_WAIT_V(8); PG8_WAIT_L(0); PG8_BAR; PG8_MMA(1, 0, At, B0); PG8_MMA(1, 1, At, B1); PG8_BAR; PG8_SCHED;
.LBB0_408:
	s_ashr_i32 s11, s10, 31
	s_lshl_b64 s[12:13], s[10:11], 19
	s_add_u32 s12, s30, s12
	s_addc_u32 s13, s31, s13
	s_and_b64 s[18:19], s[4:5], exec
	s_cselect_b32 s11, s13, s23
	s_cselect_b32 s53, s12, s22
	s_ashr_i32 s9, s8, 31
	s_lshl_b64 s[18:19], s[8:9], 19
	s_add_u32 s18, s37, s18
	s_addc_u32 s19, s44, s19
	s_and_b64 s[26:27], s[4:5], exec
	s_cselect_b32 s9, s19, s25
	s_cselect_b32 s54, s18, s24
	s_add_u32 s55, s24, 0x100
	s_addc_u32 s56, s25, 0
	s_mov_b32 s57, -2
	s_add_u32 s24, s22, 0x8000
	s_addc_u32 s25, s23, 0
	s_cmp_eq_u32 s57, 12
	s_cselect_b32 s42, s53, s24
	s_cselect_b32 s43, s11, s25
	s_cselect_b32 s40, s54, s55
	s_cselect_b32 s41, s9, s56
	s_add_u32 s26, s42, 0x4000
	s_addc_u32 s27, s43, 0
	v_add_u32_e32 v145, s76, v142
	s_add_i32 s58, 0, 0x14000
	ds_read_b128 v[146:149], v145
	ds_read_b128 v[150:153], v145 offset:1024
	ds_read_b128 v[160:163], v145 offset:2048
	ds_read_b128 v[164:167], v145 offset:3072
	v_add_u32_e32 v145, s58, v142
	ds_read_b128 v[168:171], v145
	ds_read_b128 v[172:175], v145 offset:1024
	ds_read_b128 v[176:179], v145 offset:2048
	ds_read_b128 v[180:183], v145 offset:3072
	v_lshl_add_u64 v[230:231], s[22:23], 0, v[140:141]
	s_add_i32 m0, s45, 0xc000
	ds_read_b128 v[184:187], v144
	ds_read_b128 v[188:191], v144 offset:1024
	ds_read_b128 v[206:209], v144 offset:2048
	ds_read_b128 v[210:213], v144 offset:3072
	ds_read_b128 v[214:217], v144 offset:4096
	ds_read_b128 v[218:221], v144 offset:5120
	ds_read_b128 v[222:225], v144 offset:6144
	ds_read_b128 v[226:229], v144 offset:7168
	global_load_lds_dwordx4 v[230:231], off
	v_lshl_add_u64 v[230:231], s[22:23], 0, v[138:139]
	s_add_i32 m0, s45, 0xe000
	s_nop 0
	global_load_lds_dwordx4 v[230:231], off
	s_waitcnt vmcnt(16)
	s_waitcnt lgkmcnt(0)
	s_barrier
	v_mfma_f32_16x16x32_bf16 v[126:129], v[146:149], v[184:187], 0
	v_mfma_f32_16x16x32_bf16 v[126:129], v[150:153], v[188:191], v[126:129]
	v_mfma_f32_16x16x32_bf16 v[118:121], v[164:167], v[188:191], 0
	v_mfma_f32_16x16x32_bf16 v[118:121], v[160:163], v[184:187], v[118:121]
	v_mfma_f32_16x16x32_bf16 v[102:105], v[160:163], v[206:209], 0
	v_mfma_f32_16x16x32_bf16 v[102:105], v[164:167], v[210:213], v[102:105]
	v_mfma_f32_16x16x32_bf16 v[110:113], v[150:153], v[210:213], 0
	v_mfma_f32_16x16x32_bf16 v[110:113], v[146:149], v[206:209], v[110:113]
	v_mfma_f32_16x16x32_bf16 v[94:97], v[146:149], v[214:217], 0
	v_mfma_f32_16x16x32_bf16 v[94:97], v[150:153], v[218:221], v[94:97]
	v_mfma_f32_16x16x32_bf16 v[86:89], v[164:167], v[218:221], 0
	v_mfma_f32_16x16x32_bf16 v[86:89], v[160:163], v[214:217], v[86:89]
	v_mfma_f32_16x16x32_bf16 v[70:73], v[160:163], v[222:225], 0
	v_mfma_f32_16x16x32_bf16 v[70:73], v[164:167], v[226:229], v[70:73]
	v_mfma_f32_16x16x32_bf16 v[78:81], v[150:153], v[226:229], 0
	v_mfma_f32_16x16x32_bf16 v[78:81], v[146:149], v[222:225], v[78:81]
	v_mfma_f32_16x16x32_bf16 v[122:125], v[168:171], v[184:187], 0
	v_mfma_f32_16x16x32_bf16 v[122:125], v[172:175], v[188:191], v[122:125]
	v_mfma_f32_16x16x32_bf16 v[114:117], v[180:183], v[188:191], 0
	v_mfma_f32_16x16x32_bf16 v[114:117], v[176:179], v[184:187], v[114:117]
	v_mfma_f32_16x16x32_bf16 v[98:101], v[176:179], v[206:209], 0
	v_mfma_f32_16x16x32_bf16 v[98:101], v[180:183], v[210:213], v[98:101]
	v_mfma_f32_16x16x32_bf16 v[106:109], v[172:175], v[210:213], 0
	v_mfma_f32_16x16x32_bf16 v[106:109], v[168:171], v[206:209], v[106:109]
	v_mfma_f32_16x16x32_bf16 v[90:93], v[168:171], v[214:217], 0
	v_mfma_f32_16x16x32_bf16 v[90:93], v[172:175], v[218:221], v[90:93]
	v_mfma_f32_16x16x32_bf16 v[82:85], v[180:183], v[218:221], 0
	v_mfma_f32_16x16x32_bf16 v[82:85], v[176:179], v[214:217], v[82:85]
	v_mfma_f32_16x16x32_bf16 v[66:69], v[176:179], v[222:225], 0
	v_mfma_f32_16x16x32_bf16 v[66:69], v[180:183], v[226:229], v[66:69]
	v_mfma_f32_16x16x32_bf16 v[74:77], v[172:175], v[226:229], 0
	v_mfma_f32_16x16x32_bf16 v[74:77], v[168:171], v[222:225], v[74:77]
	s_barrier
	s_add_i32 s22, s76, s29
	v_lshl_add_u64 v[230:231], s[40:41], 0, v[0:1]
	s_mov_b32 m0, s22
	ds_read_b128 v[184:187], v144 offset:16384
	ds_read_b128 v[188:191], v144 offset:17408
	ds_read_b128 v[206:209], v144 offset:18432
	ds_read_b128 v[210:213], v144 offset:19456
	ds_read_b128 v[214:217], v144 offset:20480
	ds_read_b128 v[218:221], v144 offset:21504
	ds_read_b128 v[222:225], v144 offset:22528
	ds_read_b128 v[226:229], v144 offset:23552
	global_load_lds_dwordx4 v[230:231], off
	s_add_i32 m0, s22, 0x2000
	s_add_u32 s22, s40, 0x40000
	v_lshl_add_u64 v[232:233], s[40:41], 0, v[130:131]
	s_addc_u32 s23, s41, 0
	s_add_i32 s58, s58, s29
	global_load_lds_dwordx4 v[232:233], off
	v_lshl_add_u64 v[234:235], s[22:23], 0, v[0:1]
	s_mov_b32 m0, s58
	s_nop 0
	global_load_lds_dwordx4 v[234:235], off
	v_lshl_add_u64 v[234:235], s[22:23], 0, v[130:131]
	s_add_i32 m0, s58, 0x2000
	s_nop 0
	global_load_lds_dwordx4 v[234:235], off
	v_lshl_add_u64 v[234:235], s[42:43], 0, v[134:135]
	s_mov_b32 m0, s45
	s_nop 0
	global_load_lds_dwordx4 v[234:235], off
	v_lshl_add_u64 v[234:235], s[42:43], 0, v[132:133]
	s_mov_b32 m0, s46
	s_nop 0
	global_load_lds_dwordx4 v[234:235], off
	s_waitcnt vmcnt(16)
	s_waitcnt lgkmcnt(0)
	s_barrier
; #define PG8_STAGE(bufoff, gbase, voff) do { _Pragma("unroll") for (int _i = 0; _i < 2; ++_i) \
;         __builtin_amdgcn_global_load_lds((const unsigned*)((const char*)(gbase) + (voff)[_i]), (PG8_LAS unsigned*)(lds + (bufoff) + ldsw + _i * 8192), 16, 0, 0); } while (0)
; #define PG8_LDA(dst, b, h) do { _Pragma("unroll") for (int m = 0; m < 4; ++m) _Pragma("unroll") for (int k = 0; k < 2; ++k) dst[m][k] = *(const PG8_LAS bf16x8*)(lds + PG8_SA(b, h) + aoff + m * 2048 + k * 1024); } while (0)
; #define PG8_LDB(dst, b, h) do { _Pragma("unroll") for (int n = 0; n < 2; ++n) _Pragma("unroll") for (int k = 0; k < 2; ++k) dst[n][k] = *(const PG8_LAS bf16x8*)(lds + PG8_SB(b, h) + boff + n * 2048 + k * 1024); } while (0)
; #define PG8_MMA(ai, bj, At, Bt) do { __builtin_amdgcn_s_setprio(1); _Pragma("unroll") for (int m = 0; m < 4; ++m) _Pragma("unroll") for (int n = 0; n < 2; ++n) _Pragma("unroll") for (int k = 0; k < 2; ++k) \
;         acc[ai][bj][m][n] = __builtin_amdgcn_mfma_f32_16x16x32_bf16(Bt[n][k], At[m][k], acc[ai][bj][m][n], 0, 0, 0); __builtin_amdgcn_s_setprio(0); } while (0)
; #define PG8_WAIT_V(n) asm volatile("s_waitcnt vmcnt(" #n ")" ::: "memory")
; #define PG8_WAIT_L(n) asm volatile("s_waitcnt lgkmcnt(" #n ")" ::: "memory")
; #define PG8_BAR __builtin_amdgcn_s_barrier()
; #define PG8_SCHED __builtin_amdgcn_sched_barrier(0)
; template <class Epi, class Sched, bool ALIGN_EPI = false, bool SP2 = false>
; __device__ __forceinline__ void gemm_phase(PG8_LAS unsigned char* lds, const Gemm g, const Sched& S, const Epi& E) {
;     ...
;             PG8_WAIT_V(8); PG8_WAIT_L(0); PG8_BAR; PG8_MMA(1, 0, At, B0); PG8_MMA(1, 1, At, B1); PG8_BAR; PG8_SCHED;
;             PG8_LDB(B0, 1, 0); PG8_LDB(B1, 1, 1); PG8_SCHED; PG8_LDA(At, 1, 0); PG8_STAGE(PG8_SA(0, 1), a2 + hstep, voffA);
;             PG8_WAIT_V(8); PG8_WAIT_L(0); PG8_BAR; PG8_MMA(0, 0, At, B0); PG8_MMA(0, 1, At, B1); PG8_BAR; PG8_SCHED;
	v_mfma_f32_16x16x32_bf16 v[62:65], v[146:149], v[184:187], 0
	v_mfma_f32_16x16x32_bf16 v[62:65], v[150:153], v[188:191], v[62:65]
	v_mfma_f32_16x16x32_bf16 v[54:57], v[164:167], v[188:191], 0
	v_mfma_f32_16x16x32_bf16 v[54:57], v[160:163], v[184:187], v[54:57]
	v_mfma_f32_16x16x32_bf16 v[38:41], v[160:163], v[206:209], 0
	v_mfma_f32_16x16x32_bf16 v[38:41], v[164:167], v[210:213], v[38:41]
	v_mfma_f32_16x16x32_bf16 v[46:49], v[150:153], v[210:213], 0
	v_mfma_f32_16x16x32_bf16 v[46:49], v[146:149], v[206:209], v[46:49]
	v_mfma_f32_16x16x32_bf16 v[30:33], v[146:149], v[214:217], 0
	v_mfma_f32_16x16x32_bf16 v[30:33], v[150:153], v[218:221], v[30:33]
	v_mfma_f32_16x16x32_bf16 v[22:25], v[164:167], v[218:221], 0
	v_mfma_f32_16x16x32_bf16 v[22:25], v[160:163], v[214:217], v[22:25]
	v_mfma_f32_16x16x32_bf16 v[6:9], v[160:163], v[222:225], 0
	v_mfma_f32_16x16x32_bf16 v[6:9], v[164:167], v[226:229], v[6:9]
	v_mfma_f32_16x16x32_bf16 v[14:17], v[150:153], v[226:229], 0
	v_mfma_f32_16x16x32_bf16 v[14:17], v[146:149], v[222:225], v[14:17]
	v_mfma_f32_16x16x32_bf16 v[58:61], v[168:171], v[184:187], 0
	v_mfma_f32_16x16x32_bf16 v[58:61], v[172:175], v[188:191], v[58:61]
	v_mfma_f32_16x16x32_bf16 v[50:53], v[180:183], v[188:191], 0
	v_mfma_f32_16x16x32_bf16 v[50:53], v[176:179], v[184:187], v[50:53]
	v_mfma_f32_16x16x32_bf16 v[34:37], v[176:179], v[206:209], 0
	v_mfma_f32_16x16x32_bf16 v[34:37], v[180:183], v[210:213], v[34:37]
	v_mfma_f32_16x16x32_bf16 v[42:45], v[172:175], v[210:213], 0
	v_mfma_f32_16x16x32_bf16 v[42:45], v[168:171], v[206:209], v[42:45]
	v_mfma_f32_16x16x32_bf16 v[26:29], v[168:171], v[214:217], 0
	v_mfma_f32_16x16x32_bf16 v[26:29], v[172:175], v[218:221], v[26:29]
	v_mfma_f32_16x16x32_bf16 v[18:21], v[180:183], v[218:221], 0
	v_mfma_f32_16x16x32_bf16 v[18:21], v[176:179], v[214:217], v[18:21]
	v_mfma_f32_16x16x32_bf16 v[2:5], v[176:179], v[222:225], 0
	v_mfma_f32_16x16x32_bf16 v[2:5], v[180:183], v[226:229], v[2:5]
	v_mfma_f32_16x16x32_bf16 v[10:13], v[172:175], v[226:229], 0
	v_mfma_f32_16x16x32_bf16 v[10:13], v[168:171], v[222:225], v[10:13]
	s_barrier
	s_add_i32 s58, 0, 0x18000
	v_add_u32_e32 v145, s58, v142
	s_add_i32 s59, 0, 0x1c000
	ds_read_b128 v[146:149], v145
	ds_read_b128 v[150:153], v145 offset:1024
	ds_read_b128 v[160:163], v145 offset:2048
	ds_read_b128 v[164:167], v145 offset:3072
	v_add_u32_e32 v145, s59, v142
	ds_read_b128 v[168:171], v145
	ds_read_b128 v[172:175], v145 offset:1024
	ds_read_b128 v[176:179], v145 offset:2048
	ds_read_b128 v[180:183], v145 offset:3072
	s_add_u32 s22, s42, 0x40000
	s_addc_u32 s23, s43, 0
	s_mov_b32 m0, s47
	v_lshl_add_u64 v[234:235], s[22:23], 0, v[134:135]
	ds_read_b128 v[184:187], v144 offset:32768
	ds_read_b128 v[188:191], v144 offset:33792
	ds_read_b128 v[206:209], v144 offset:34816
	ds_read_b128 v[210:213], v144 offset:35840
	ds_read_b128 v[214:217], v144 offset:36864
	ds_read_b128 v[218:221], v144 offset:37888
	ds_read_b128 v[222:225], v144 offset:38912
	ds_read_b128 v[226:229], v144 offset:39936
	global_load_lds_dwordx4 v[234:235], off
	v_lshl_add_u64 v[234:235], s[22:23], 0, v[132:133]
	s_mov_b32 m0, s48
	s_nop 0
	global_load_lds_dwordx4 v[234:235], off
	s_waitcnt vmcnt(8)
	s_waitcnt lgkmcnt(0)
	s_barrier
	v_mfma_f32_16x16x32_bf16 v[126:129], v[146:149], v[184:187], v[126:129]
	v_mfma_f32_16x16x32_bf16 v[126:129], v[150:153], v[188:191], v[126:129]
	v_mfma_f32_16x16x32_bf16 v[118:121], v[164:167], v[188:191], v[118:121]
	v_mfma_f32_16x16x32_bf16 v[118:121], v[160:163], v[184:187], v[118:121]
	v_mfma_f32_16x16x32_bf16 v[102:105], v[160:163], v[206:209], v[102:105]
	v_mfma_f32_16x16x32_bf16 v[102:105], v[164:167], v[210:213], v[102:105]
	v_mfma_f32_16x16x32_bf16 v[110:113], v[150:153], v[210:213], v[110:113]
	v_mfma_f32_16x16x32_bf16 v[110:113], v[146:149], v[206:209], v[110:113]
	v_mfma_f32_16x16x32_bf16 v[94:97], v[146:149], v[214:217], v[94:97]
	v_mfma_f32_16x16x32_bf16 v[94:97], v[150:153], v[218:221], v[94:97]
	v_mfma_f32_16x16x32_bf16 v[86:89], v[164:167], v[218:221], v[86:89]
	v_mfma_f32_16x16x32_bf16 v[86:89], v[160:163], v[214:217], v[86:89]
	v_mfma_f32_16x16x32_bf16 v[70:73], v[160:163], v[222:225], v[70:73]
	v_mfma_f32_16x16x32_bf16 v[70:73], v[164:167], v[226:229], v[70:73]
	v_mfma_f32_16x16x32_bf16 v[78:81], v[150:153], v[226:229], v[78:81]
	v_mfma_f32_16x16x32_bf16 v[78:81], v[146:149], v[222:225], v[78:81]
	v_mfma_f32_16x16x32_bf16 v[122:125], v[168:171], v[184:187], v[122:125]
	v_mfma_f32_16x16x32_bf16 v[122:125], v[172:175], v[188:191], v[122:125]
	v_mfma_f32_16x16x32_bf16 v[114:117], v[180:183], v[188:191], v[114:117]
	v_mfma_f32_16x16x32_bf16 v[114:117], v[176:179], v[184:187], v[114:117]
	v_mfma_f32_16x16x32_bf16 v[98:101], v[176:179], v[206:209], v[98:101]
	v_mfma_f32_16x16x32_bf16 v[98:101], v[180:183], v[210:213], v[98:101]
	v_mfma_f32_16x16x32_bf16 v[106:109], v[172:175], v[210:213], v[106:109]
	v_mfma_f32_16x16x32_bf16 v[106:109], v[168:171], v[206:209], v[106:109]
	v_mfma_f32_16x16x32_bf16 v[90:93], v[168:171], v[214:217], v[90:93]
	v_mfma_f32_16x16x32_bf16 v[90:93], v[172:175], v[218:221], v[90:93]
	v_mfma_f32_16x16x32_bf16 v[82:85], v[180:183], v[218:221], v[82:85]
	v_mfma_f32_16x16x32_bf16 v[82:85], v[176:179], v[214:217], v[82:85]
	v_mfma_f32_16x16x32_bf16 v[66:69], v[176:179], v[222:225], v[66:69]
	v_mfma_f32_16x16x32_bf16 v[66:69], v[180:183], v[226:229], v[66:69]
	v_mfma_f32_16x16x32_bf16 v[74:77], v[172:175], v[226:229], v[74:77]
	v_mfma_f32_16x16x32_bf16 v[74:77], v[168:171], v[222:225], v[74:77]
	s_barrier
; #define PG8_STAGE(bufoff, gbase, voff) do { _Pragma("unroll") for (int _i = 0; _i < 2; ++_i) \
;         __builtin_amdgcn_global_load_lds((const unsigned*)((const char*)(gbase) + (voff)[_i]), (PG8_LAS unsigned*)(lds + (bufoff) + ldsw + _i * 8192), 16, 0, 0); } while (0)
; #define PG8_LDA(dst, b, h) do { _Pragma("unroll") for (int m = 0; m < 4; ++m) _Pragma("unroll") for (int k = 0; k < 2; ++k) dst[m][k] = *(const PG8_LAS bf16x8*)(lds + PG8_SA(b, h) + aoff + m * 2048 + k * 1024); } while (0)
; #define PG8_MMA(ai, bj, At, Bt) do { __builtin_amdgcn_s_setprio(1); _Pragma("unroll") for (int m = 0; m < 4; ++m) _Pragma("unroll") for (int n = 0; n < 2; ++n) _Pragma("unroll") for (int k = 0; k < 2; ++k) \
;         acc[ai][bj][m][n] = __builtin_amdgcn_mfma_f32_16x16x32_bf16(Bt[n][k], At[m][k], acc[ai][bj][m][n], 0, 0, 0); __builtin_amdgcn_s_setprio(0); } while (0)
; #define PG8_WAIT_V(n) asm volatile("s_waitcnt vmcnt(" #n ")" ::: "memory")
; #define PG8_WAIT_L(n) asm volatile("s_waitcnt lgkmcnt(" #n ")" ::: "memory")
; #define PG8_BAR __builtin_amdgcn_s_barrier()
; #define PG8_SCHED __builtin_amdgcn_sched_barrier(0)
; template <class Epi, class Sched, bool ALIGN_EPI = false, bool SP2 = false>
; __device__ __forceinline__ void gemm_phase(PG8_LAS unsigned char* lds, const Gemm g, const Sched& S, const Epi& E) {
;     ...
;         for (int t = 0; t < nt; t += 2) {
;     ...
;             PG8_LDA(At, 1, 1); PG8_STAGE(PG8_SB(1, 0), b3, voffB); PG8_STAGE(PG8_SB(1, 1), b3 + hstep, voffB); PG8_STAGE(PG8_SA(1, 0), a3, voffA);
;             PG8_WAIT_V(8); PG8_WAIT_L(0); PG8_BAR; PG8_MMA(1, 0, At, B0); PG8_MMA(1, 1, At, B1); PG8_BAR; PG8_SCHED;
	s_add_i32 s22, s58, s29
	v_lshl_add_u64 v[230:231], v[230:231], 0, s[38:39]
	s_mov_b32 m0, s22
	ds_read_b128 v[184:187], v144 offset:49152
	ds_read_b128 v[188:191], v144 offset:50176
	ds_read_b128 v[206:209], v144 offset:51200
	ds_read_b128 v[210:213], v144 offset:52224
	ds_read_b128 v[214:217], v144 offset:53248
	ds_read_b128 v[218:221], v144 offset:54272
	ds_read_b128 v[222:225], v144 offset:55296
	ds_read_b128 v[226:229], v144 offset:56320
	global_load_lds_dwordx4 v[230:231], off
	s_add_i32 m0, s22, 0x2000
	s_add_u32 s22, s40, 0x40080
	v_lshl_add_u64 v[230:231], v[232:233], 0, s[38:39]
	s_addc_u32 s23, s41, 0
	s_add_i32 s40, s59, s29
	global_load_lds_dwordx4 v[230:231], off
	v_lshl_add_u64 v[230:231], s[22:23], 0, v[0:1]
	s_mov_b32 m0, s40
	s_nop 0
	global_load_lds_dwordx4 v[230:231], off
	v_lshl_add_u64 v[230:231], s[22:23], 0, v[130:131]
	s_add_i32 m0, s40, 0x2000
	s_nop 0
	global_load_lds_dwordx4 v[230:231], off
	v_lshl_add_u64 v[230:231], s[26:27], 0, v[134:135]
	s_mov_b32 m0, s49
	s_nop 0
	global_load_lds_dwordx4 v[230:231], off
	v_lshl_add_u64 v[230:231], s[26:27], 0, v[132:133]
	s_mov_b32 m0, s50
	s_nop 0
	global_load_lds_dwordx4 v[230:231], off
	s_waitcnt vmcnt(8)
	s_waitcnt lgkmcnt(0)
	s_barrier
	v_mfma_f32_16x16x32_bf16 v[62:65], v[146:149], v[184:187], v[62:65]
	v_mfma_f32_16x16x32_bf16 v[62:65], v[150:153], v[188:191], v[62:65]
	v_mfma_f32_16x16x32_bf16 v[54:57], v[164:167], v[188:191], v[54:57]
	v_mfma_f32_16x16x32_bf16 v[54:57], v[160:163], v[184:187], v[54:57]
	v_mfma_f32_16x16x32_bf16 v[38:41], v[160:163], v[206:209], v[38:41]
	v_mfma_f32_16x16x32_bf16 v[38:41], v[164:167], v[210:213], v[38:41]
	v_mfma_f32_16x16x32_bf16 v[46:49], v[150:153], v[210:213], v[46:49]
	v_mfma_f32_16x16x32_bf16 v[46:49], v[146:149], v[206:209], v[46:49]
	v_mfma_f32_16x16x32_bf16 v[30:33], v[146:149], v[214:217], v[30:33]
	v_mfma_f32_16x16x32_bf16 v[30:33], v[150:153], v[218:221], v[30:33]
	v_mfma_f32_16x16x32_bf16 v[22:25], v[164:167], v[218:221], v[22:25]
	v_mfma_f32_16x16x32_bf16 v[22:25], v[160:163], v[214:217], v[22:25]
	v_mfma_f32_16x16x32_bf16 v[6:9], v[160:163], v[222:225], v[6:9]
	v_mfma_f32_16x16x32_bf16 v[6:9], v[164:167], v[226:229], v[6:9]
	v_mfma_f32_16x16x32_bf16 v[14:17], v[150:153], v[226:229], v[14:17]
	v_mfma_f32_16x16x32_bf16 v[14:17], v[146:149], v[222:225], v[14:17]
	v_mfma_f32_16x16x32_bf16 v[58:61], v[168:171], v[184:187], v[58:61]
	v_mfma_f32_16x16x32_bf16 v[58:61], v[172:175], v[188:191], v[58:61]
	v_mfma_f32_16x16x32_bf16 v[50:53], v[180:183], v[188:191], v[50:53]
	v_mfma_f32_16x16x32_bf16 v[50:53], v[176:179], v[184:187], v[50:53]
	v_mfma_f32_16x16x32_bf16 v[34:37], v[176:179], v[206:209], v[34:37]
	v_mfma_f32_16x16x32_bf16 v[34:37], v[180:183], v[210:213], v[34:37]
	v_mfma_f32_16x16x32_bf16 v[42:45], v[172:175], v[210:213], v[42:45]
	v_mfma_f32_16x16x32_bf16 v[42:45], v[168:171], v[206:209], v[42:45]
	v_mfma_f32_16x16x32_bf16 v[26:29], v[168:171], v[214:217], v[26:29]
	v_mfma_f32_16x16x32_bf16 v[26:29], v[172:175], v[218:221], v[26:29]
	v_mfma_f32_16x16x32_bf16 v[18:21], v[180:183], v[218:221], v[18:21]
	v_mfma_f32_16x16x32_bf16 v[18:21], v[176:179], v[214:217], v[18:21]
	v_mfma_f32_16x16x32_bf16 v[2:5], v[176:179], v[222:225], v[2:5]
	v_mfma_f32_16x16x32_bf16 v[2:5], v[180:183], v[226:229], v[2:5]
	v_mfma_f32_16x16x32_bf16 v[10:13], v[172:175], v[226:229], v[10:13]
	v_mfma_f32_16x16x32_bf16 v[10:13], v[168:171], v[222:225], v[10:13]
	s_barrier
	s_add_i32 s57, s57, 2
	s_add_u32 s55, s55, 0x100
	s_addc_u32 s56, s56, 0
	s_cmp_gt_u32 s57, 13
	s_mov_b64 s[22:23], s[24:25]
	s_cbranch_scc1 .Lpeel_exit_2
	.p2align 6
